# pooled weight fold: item index permuted so a workgroup's 8 waves share the n-block and window group (w_pool_out reads hit the CU's L1)
# speedup vs baseline: 1.0143x; 1.0032x over previous
; #define LAS __attribute__((address_space(3)))
; #define LDS_WAIT() asm volatile("s_waitcnt lgkmcnt(0)" ::: "memory")
; __global__ void __launch_bounds__(NTHREADS, 2) mk_fwd(Args args) {
;     ...
;             for (int it = gw; it < 128 * 16; it += NGW) {
;                 const int kb = it >> 4, nb = it & 15, k0 = kb * 4, g = k0 >> 7, c0 = k0 & 127, n = nb * 64 + lane;
;                 { const f32x2 sc = *(const f32x2*)(psc + g * 128 + 2 * lane);
; #pragma unroll
;                   for (int j = 0; j < 4; ++j) { const f32x2 v = *(const f32x2*)(pw + (size_t)(g * 128 + c0 + j) * 128 + 2 * lane); *(LAS f32x2*)(scr + j * 128 + 2 * lane) = (f32x2){v.x * sc.x, v.y * sc.y}; } }
;                 LDS_WAIT(); asm volatile("" ::: "memory");
;                 float a4[4];
; #pragma unroll
;                 for (int j = 0; j < 4; ++j) a4[j] = 0.f;
; #pragma unroll 1
;                 for (int d0 = 0; d0 < 128; d0 += 32) {
;                     float wv[32];
; #pragma unroll
;                     for (int d = 0; d < 32; ++d) wv[d] = wpo[(size_t)(g * 128 + d0 + d) * DM + n];
; #pragma unroll
;                     for (int d = 0; d < 32; d += 4)
; #pragma unroll
;                         for (int j = 0; j < 4; ++j) { const f32x4 pv = *(const LAS f32x4*)(scr + j * 128 + d0 + d); a4[j] += (pv.x * wv[d] + pv.y * wv[d + 1]) + (pv.z * wv[d + 2] + pv.w * wv[d + 3]); } }
.LBB0_617:
	s_lshl_b32 s2, s15, 5
	s_and_b32 s2, s2, 0xf00
	v_lshl_or_b32 v32, v71, 2, s2
	s_lshr_b32 s2, s15, 7
	s_and_b32 s17, s15, 7
	s_lshl_b32 s2, s2, 3
	s_or_b32 s2, s2, s17
	s_lshl_b32 s2, s2, 2
	s_mov_b32 s3, 0
	s_mov_b32 s17, s2
	s_lshl_b64 s[20:21], s[2:3], 9
	s_and_b32 s18, s17, 0xffffff80
	s_ashr_i32 s19, s18, 31
	v_lshl_add_u64 v[64:65], v[36:37], 0, s[20:21]
	v_lshl_add_u64 v[66:67], s[18:19], 2, v[34:35]
	global_load_dwordx2 v[38:39], v[66:67], off
	global_load_dwordx2 v[46:47], v[64:65], off
	global_load_dwordx2 v[48:49], v[64:65], off offset:512
	global_load_dwordx2 v[50:51], v[64:65], off offset:1024
	global_load_dwordx2 v[52:53], v[64:65], off offset:1536
	s_lshl_b64 s[18:19], s[18:19], 12
	s_add_u32 s18, s12, s18
	s_addc_u32 s19, s13, s19
	v_lshl_add_u32 v62, v71, 5, s34
	v_mov_b32_e32 v63, s34
	v_mov_b32_e32 v40, 0
	v_mov_b32_e32 v41, 0
	v_mov_b32_e32 v42, 0
	v_mov_b32_e32 v43, 0
	global_load_dword v82, v32, s[18:19]
	s_add_u32 s18, s18, 0x1000
	s_addc_u32 s19, s19, 0
	global_load_dword v83, v32, s[18:19]
	s_add_u32 s18, s18, 0x1000
	s_addc_u32 s19, s19, 0
	global_load_dword v84, v32, s[18:19]
	s_add_u32 s18, s18, 0x1000
	s_addc_u32 s19, s19, 0
	global_load_dword v85, v32, s[18:19]
	s_add_u32 s18, s18, 0x1000
	s_addc_u32 s19, s19, 0
	global_load_dword v86, v32, s[18:19]
	s_add_u32 s18, s18, 0x1000
	s_addc_u32 s19, s19, 0
	global_load_dword v87, v32, s[18:19]
	s_add_u32 s18, s18, 0x1000
	s_addc_u32 s19, s19, 0
	global_load_dword v88, v32, s[18:19]
	s_add_u32 s18, s18, 0x1000
	s_addc_u32 s19, s19, 0
	global_load_dword v89, v32, s[18:19]
	s_add_u32 s18, s18, 0x1000
	s_addc_u32 s19, s19, 0
	global_load_dword v90, v32, s[18:19]
	s_add_u32 s18, s18, 0x1000
	s_addc_u32 s19, s19, 0
	global_load_dword v91, v32, s[18:19]
	s_add_u32 s18, s18, 0x1000
	s_addc_u32 s19, s19, 0
	global_load_dword v92, v32, s[18:19]
	s_add_u32 s18, s18, 0x1000
	s_addc_u32 s19, s19, 0
	global_load_dword v93, v32, s[18:19]
	s_add_u32 s18, s18, 0x1000
	s_addc_u32 s19, s19, 0
	global_load_dword v94, v32, s[18:19]
	s_add_u32 s18, s18, 0x1000
	s_addc_u32 s19, s19, 0
	global_load_dword v95, v32, s[18:19]
	s_add_u32 s18, s18, 0x1000
	s_addc_u32 s19, s19, 0
	global_load_dword v96, v32, s[18:19]
	s_add_u32 s18, s18, 0x1000
	s_addc_u32 s19, s19, 0
	global_load_dword v97, v32, s[18:19]
	s_add_u32 s18, s18, 0x1000
	s_addc_u32 s19, s19, 0
	global_load_dword v98, v32, s[18:19]
	s_add_u32 s18, s18, 0x1000
	s_addc_u32 s19, s19, 0
	global_load_dword v99, v32, s[18:19]
	s_add_u32 s18, s18, 0x1000
	s_addc_u32 s19, s19, 0
	global_load_dword v100, v32, s[18:19]
	s_add_u32 s18, s18, 0x1000
	s_addc_u32 s19, s19, 0
	global_load_dword v101, v32, s[18:19]
	s_add_u32 s18, s18, 0x1000
	s_addc_u32 s19, s19, 0
	global_load_dword v102, v32, s[18:19]
	s_add_u32 s18, s18, 0x1000
	s_addc_u32 s19, s19, 0
	global_load_dword v103, v32, s[18:19]
	s_add_u32 s18, s18, 0x1000
	s_addc_u32 s19, s19, 0
	global_load_dword v104, v32, s[18:19]
	s_add_u32 s18, s18, 0x1000
	s_addc_u32 s19, s19, 0
	global_load_dword v105, v32, s[18:19]
	s_add_u32 s18, s18, 0x1000
	s_addc_u32 s19, s19, 0
	global_load_dword v106, v32, s[18:19]
	s_add_u32 s18, s18, 0x1000
	s_addc_u32 s19, s19, 0
	global_load_dword v107, v32, s[18:19]
	s_add_u32 s18, s18, 0x1000
	s_addc_u32 s19, s19, 0
	global_load_dword v108, v32, s[18:19]
	s_add_u32 s18, s18, 0x1000
	s_addc_u32 s19, s19, 0
	global_load_dword v109, v32, s[18:19]
	s_add_u32 s18, s18, 0x1000
	s_addc_u32 s19, s19, 0
	global_load_dword v110, v32, s[18:19]
	s_add_u32 s18, s18, 0x1000
	s_addc_u32 s19, s19, 0
	global_load_dword v111, v32, s[18:19]
	s_add_u32 s18, s18, 0x1000
	s_addc_u32 s19, s19, 0
	global_load_dword v112, v32, s[18:19]
	s_add_u32 s18, s18, 0x1000
	s_addc_u32 s19, s19, 0
	global_load_dword v113, v32, s[18:19]
	s_add_u32 s18, s18, 0x1000
	s_addc_u32 s19, s19, 0
	s_waitcnt vmcnt(32)
	v_mul_f32_e32 v54, v38, v46
	v_mul_f32_e32 v58, v39, v47
	v_mul_f32_e32 v55, v38, v48
	v_mul_f32_e32 v59, v39, v49
	v_mul_f32_e32 v56, v38, v50
	v_mul_f32_e32 v60, v39, v51
	v_mul_f32_e32 v57, v38, v52
	v_mul_f32_e32 v61, v39, v53
	ds_write_b128 v62, v[54:57]
	ds_write_b128 v62, v[58:61] offset:16
	s_waitcnt lgkmcnt(0)
	ds_read_b128 v[114:117], v63 offset:0
	ds_read_b128 v[118:121], v63 offset:16
	ds_read_b128 v[122:125], v63 offset:32
	ds_read_b128 v[126:129], v63 offset:48
	s_waitcnt vmcnt(31) lgkmcnt(3)
	v_pk_fma_f32 v[40:41], v[114:115], v[82:83], v[40:41] op_sel_hi:[1,0,1]
	v_pk_fma_f32 v[42:43], v[116:117], v[82:83], v[42:43] op_sel_hi:[1,0,1]
	global_load_dword v82, v32, s[18:19]
	s_add_u32 s18, s18, 0x1000
	s_addc_u32 s19, s19, 0
	ds_read_b128 v[114:117], v63 offset:64
	s_waitcnt vmcnt(31) lgkmcnt(3)
	v_pk_fma_f32 v[40:41], v[118:119], v[82:83], v[40:41] op_sel:[0,1,0] op_sel_hi:[1,1,1]
	v_pk_fma_f32 v[42:43], v[120:121], v[82:83], v[42:43] op_sel:[0,1,0] op_sel_hi:[1,1,1]
	global_load_dword v83, v32, s[18:19]
	s_add_u32 s18, s18, 0x1000
	s_addc_u32 s19, s19, 0
	ds_read_b128 v[118:121], v63 offset:80
	s_waitcnt vmcnt(31) lgkmcnt(3)
	v_pk_fma_f32 v[40:41], v[122:123], v[84:85], v[40:41] op_sel_hi:[1,0,1]
	v_pk_fma_f32 v[42:43], v[124:125], v[84:85], v[42:43] op_sel_hi:[1,0,1]
	global_load_dword v84, v32, s[18:19]
	s_add_u32 s18, s18, 0x1000
	s_addc_u32 s19, s19, 0
	ds_read_b128 v[122:125], v63 offset:96
	s_waitcnt vmcnt(31) lgkmcnt(3)
	v_pk_fma_f32 v[40:41], v[126:127], v[84:85], v[40:41] op_sel:[0,1,0] op_sel_hi:[1,1,1]
	v_pk_fma_f32 v[42:43], v[128:129], v[84:85], v[42:43] op_sel:[0,1,0] op_sel_hi:[1,1,1]
	global_load_dword v85, v32, s[18:19]
	s_add_u32 s18, s18, 0x1000
	s_addc_u32 s19, s19, 0
	ds_read_b128 v[126:129], v63 offset:112
	s_waitcnt vmcnt(31) lgkmcnt(3)
; #define LAS __attribute__((address_space(3)))
; __global__ void __launch_bounds__(NTHREADS, 2) mk_fwd(Args args) {
;     ...
;                 for (int d0 = 0; d0 < 128; d0 += 32) {
;                     float wv[32];
; #pragma unroll
;                     for (int d = 0; d < 32; ++d) wv[d] = wpo[(size_t)(g * 128 + d0 + d) * DM + n];
; #pragma unroll
;                     for (int d = 0; d < 32; d += 4)
; #pragma unroll
;                         for (int j = 0; j < 4; ++j) { const f32x4 pv = *(const LAS f32x4*)(scr + j * 128 + d0 + d); a4[j] += (pv.x * wv[d] + pv.y * wv[d + 1]) + (pv.z * wv[d + 2] + pv.w * wv[d + 3]); } }
	v_pk_fma_f32 v[40:41], v[114:115], v[86:87], v[40:41] op_sel_hi:[1,0,1]
	v_pk_fma_f32 v[42:43], v[116:117], v[86:87], v[42:43] op_sel_hi:[1,0,1]
	global_load_dword v86, v32, s[18:19]
	s_add_u32 s18, s18, 0x1000
	s_addc_u32 s19, s19, 0
	ds_read_b128 v[114:117], v63 offset:128
	s_waitcnt vmcnt(31) lgkmcnt(3)
	v_pk_fma_f32 v[40:41], v[118:119], v[86:87], v[40:41] op_sel:[0,1,0] op_sel_hi:[1,1,1]
	v_pk_fma_f32 v[42:43], v[120:121], v[86:87], v[42:43] op_sel:[0,1,0] op_sel_hi:[1,1,1]
	global_load_dword v87, v32, s[18:19]
	s_add_u32 s18, s18, 0x1000
	s_addc_u32 s19, s19, 0
	ds_read_b128 v[118:121], v63 offset:144
	s_waitcnt vmcnt(31) lgkmcnt(3)
	v_pk_fma_f32 v[40:41], v[122:123], v[88:89], v[40:41] op_sel_hi:[1,0,1]
	v_pk_fma_f32 v[42:43], v[124:125], v[88:89], v[42:43] op_sel_hi:[1,0,1]
	global_load_dword v88, v32, s[18:19]
	s_add_u32 s18, s18, 0x1000
	s_addc_u32 s19, s19, 0
	ds_read_b128 v[122:125], v63 offset:160
	s_waitcnt vmcnt(31) lgkmcnt(3)
	v_pk_fma_f32 v[40:41], v[126:127], v[88:89], v[40:41] op_sel:[0,1,0] op_sel_hi:[1,1,1]
	v_pk_fma_f32 v[42:43], v[128:129], v[88:89], v[42:43] op_sel:[0,1,0] op_sel_hi:[1,1,1]
	global_load_dword v89, v32, s[18:19]
	s_add_u32 s18, s18, 0x1000
	s_addc_u32 s19, s19, 0
	ds_read_b128 v[126:129], v63 offset:176
	s_waitcnt vmcnt(31) lgkmcnt(3)
	v_pk_fma_f32 v[40:41], v[114:115], v[90:91], v[40:41] op_sel_hi:[1,0,1]
	v_pk_fma_f32 v[42:43], v[116:117], v[90:91], v[42:43] op_sel_hi:[1,0,1]
	global_load_dword v90, v32, s[18:19]
	s_add_u32 s18, s18, 0x1000
	s_addc_u32 s19, s19, 0
	ds_read_b128 v[114:117], v63 offset:192
	s_waitcnt vmcnt(31) lgkmcnt(3)
	v_pk_fma_f32 v[40:41], v[118:119], v[90:91], v[40:41] op_sel:[0,1,0] op_sel_hi:[1,1,1]
	v_pk_fma_f32 v[42:43], v[120:121], v[90:91], v[42:43] op_sel:[0,1,0] op_sel_hi:[1,1,1]
	global_load_dword v91, v32, s[18:19]
	s_add_u32 s18, s18, 0x1000
	s_addc_u32 s19, s19, 0
	ds_read_b128 v[118:121], v63 offset:208
	s_waitcnt vmcnt(31) lgkmcnt(3)
	v_pk_fma_f32 v[40:41], v[122:123], v[92:93], v[40:41] op_sel_hi:[1,0,1]
	v_pk_fma_f32 v[42:43], v[124:125], v[92:93], v[42:43] op_sel_hi:[1,0,1]
	global_load_dword v92, v32, s[18:19]
	s_add_u32 s18, s18, 0x1000
	s_addc_u32 s19, s19, 0
	ds_read_b128 v[122:125], v63 offset:224
	s_waitcnt vmcnt(31) lgkmcnt(3)
	v_pk_fma_f32 v[40:41], v[126:127], v[92:93], v[40:41] op_sel:[0,1,0] op_sel_hi:[1,1,1]
	v_pk_fma_f32 v[42:43], v[128:129], v[92:93], v[42:43] op_sel:[0,1,0] op_sel_hi:[1,1,1]
	global_load_dword v93, v32, s[18:19]
	s_add_u32 s18, s18, 0x1000
	s_addc_u32 s19, s19, 0
	ds_read_b128 v[126:129], v63 offset:240
	s_waitcnt vmcnt(31) lgkmcnt(3)
	v_pk_fma_f32 v[40:41], v[114:115], v[94:95], v[40:41] op_sel_hi:[1,0,1]
	v_pk_fma_f32 v[42:43], v[116:117], v[94:95], v[42:43] op_sel_hi:[1,0,1]
	global_load_dword v94, v32, s[18:19]
	s_add_u32 s18, s18, 0x1000
	s_addc_u32 s19, s19, 0
	ds_read_b128 v[114:117], v63 offset:256
	s_waitcnt vmcnt(31) lgkmcnt(3)
	v_pk_fma_f32 v[40:41], v[118:119], v[94:95], v[40:41] op_sel:[0,1,0] op_sel_hi:[1,1,1]
	v_pk_fma_f32 v[42:43], v[120:121], v[94:95], v[42:43] op_sel:[0,1,0] op_sel_hi:[1,1,1]
	global_load_dword v95, v32, s[18:19]
	s_add_u32 s18, s18, 0x1000
	s_addc_u32 s19, s19, 0
	ds_read_b128 v[118:121], v63 offset:272
	s_waitcnt vmcnt(31) lgkmcnt(3)
	v_pk_fma_f32 v[40:41], v[122:123], v[96:97], v[40:41] op_sel_hi:[1,0,1]
	v_pk_fma_f32 v[42:43], v[124:125], v[96:97], v[42:43] op_sel_hi:[1,0,1]
	global_load_dword v96, v32, s[18:19]
	s_add_u32 s18, s18, 0x1000
	s_addc_u32 s19, s19, 0
	ds_read_b128 v[122:125], v63 offset:288
	s_waitcnt vmcnt(31) lgkmcnt(3)
	v_pk_fma_f32 v[40:41], v[126:127], v[96:97], v[40:41] op_sel:[0,1,0] op_sel_hi:[1,1,1]
	v_pk_fma_f32 v[42:43], v[128:129], v[96:97], v[42:43] op_sel:[0,1,0] op_sel_hi:[1,1,1]
	global_load_dword v97, v32, s[18:19]
	s_add_u32 s18, s18, 0x1000
	s_addc_u32 s19, s19, 0
	ds_read_b128 v[126:129], v63 offset:304
	s_waitcnt vmcnt(31) lgkmcnt(3)
	v_pk_fma_f32 v[40:41], v[114:115], v[98:99], v[40:41] op_sel_hi:[1,0,1]
	v_pk_fma_f32 v[42:43], v[116:117], v[98:99], v[42:43] op_sel_hi:[1,0,1]
	global_load_dword v98, v32, s[18:19]
	s_add_u32 s18, s18, 0x1000
	s_addc_u32 s19, s19, 0
	ds_read_b128 v[114:117], v63 offset:320
	s_waitcnt vmcnt(31) lgkmcnt(3)
	v_pk_fma_f32 v[40:41], v[118:119], v[98:99], v[40:41] op_sel:[0,1,0] op_sel_hi:[1,1,1]
	v_pk_fma_f32 v[42:43], v[120:121], v[98:99], v[42:43] op_sel:[0,1,0] op_sel_hi:[1,1,1]
	global_load_dword v99, v32, s[18:19]
	s_add_u32 s18, s18, 0x1000
	s_addc_u32 s19, s19, 0
	ds_read_b128 v[118:121], v63 offset:336
	s_waitcnt vmcnt(31) lgkmcnt(3)
	v_pk_fma_f32 v[40:41], v[122:123], v[100:101], v[40:41] op_sel_hi:[1,0,1]
	v_pk_fma_f32 v[42:43], v[124:125], v[100:101], v[42:43] op_sel_hi:[1,0,1]
	global_load_dword v100, v32, s[18:19]
	s_add_u32 s18, s18, 0x1000
	s_addc_u32 s19, s19, 0
	ds_read_b128 v[122:125], v63 offset:352
	s_waitcnt vmcnt(31) lgkmcnt(3)
	v_pk_fma_f32 v[40:41], v[126:127], v[100:101], v[40:41] op_sel:[0,1,0] op_sel_hi:[1,1,1]
	v_pk_fma_f32 v[42:43], v[128:129], v[100:101], v[42:43] op_sel:[0,1,0] op_sel_hi:[1,1,1]
	global_load_dword v101, v32, s[18:19]
	s_add_u32 s18, s18, 0x1000
	s_addc_u32 s19, s19, 0
	ds_read_b128 v[126:129], v63 offset:368
	s_waitcnt vmcnt(31) lgkmcnt(3)
	v_pk_fma_f32 v[40:41], v[114:115], v[102:103], v[40:41] op_sel_hi:[1,0,1]
	v_pk_fma_f32 v[42:43], v[116:117], v[102:103], v[42:43] op_sel_hi:[1,0,1]
	global_load_dword v102, v32, s[18:19]
	s_add_u32 s18, s18, 0x1000
	s_addc_u32 s19, s19, 0
	ds_read_b128 v[114:117], v63 offset:384
	s_waitcnt vmcnt(31) lgkmcnt(3)
; #define LAS __attribute__((address_space(3)))
; __global__ void __launch_bounds__(NTHREADS, 2) mk_fwd(Args args) {
;     ...
;                 for (int d0 = 0; d0 < 128; d0 += 32) {
;                     float wv[32];
; #pragma unroll
;                     for (int d = 0; d < 32; ++d) wv[d] = wpo[(size_t)(g * 128 + d0 + d) * DM + n];
; #pragma unroll
;                     for (int d = 0; d < 32; d += 4)
; #pragma unroll
;                         for (int j = 0; j < 4; ++j) { const f32x4 pv = *(const LAS f32x4*)(scr + j * 128 + d0 + d); a4[j] += (pv.x * wv[d] + pv.y * wv[d + 1]) + (pv.z * wv[d + 2] + pv.w * wv[d + 3]); } }
	v_pk_fma_f32 v[40:41], v[118:119], v[102:103], v[40:41] op_sel:[0,1,0] op_sel_hi:[1,1,1]
	v_pk_fma_f32 v[42:43], v[120:121], v[102:103], v[42:43] op_sel:[0,1,0] op_sel_hi:[1,1,1]
	global_load_dword v103, v32, s[18:19]
	s_add_u32 s18, s18, 0x1000
	s_addc_u32 s19, s19, 0
	ds_read_b128 v[118:121], v63 offset:400
	s_waitcnt vmcnt(31) lgkmcnt(3)
	v_pk_fma_f32 v[40:41], v[122:123], v[104:105], v[40:41] op_sel_hi:[1,0,1]
	v_pk_fma_f32 v[42:43], v[124:125], v[104:105], v[42:43] op_sel_hi:[1,0,1]
	global_load_dword v104, v32, s[18:19]
	s_add_u32 s18, s18, 0x1000
	s_addc_u32 s19, s19, 0
	ds_read_b128 v[122:125], v63 offset:416
	s_waitcnt vmcnt(31) lgkmcnt(3)
	v_pk_fma_f32 v[40:41], v[126:127], v[104:105], v[40:41] op_sel:[0,1,0] op_sel_hi:[1,1,1]
	v_pk_fma_f32 v[42:43], v[128:129], v[104:105], v[42:43] op_sel:[0,1,0] op_sel_hi:[1,1,1]
	global_load_dword v105, v32, s[18:19]
	s_add_u32 s18, s18, 0x1000
	s_addc_u32 s19, s19, 0
	ds_read_b128 v[126:129], v63 offset:432
	s_waitcnt vmcnt(31) lgkmcnt(3)
	v_pk_fma_f32 v[40:41], v[114:115], v[106:107], v[40:41] op_sel_hi:[1,0,1]
	v_pk_fma_f32 v[42:43], v[116:117], v[106:107], v[42:43] op_sel_hi:[1,0,1]
	global_load_dword v106, v32, s[18:19]
	s_add_u32 s18, s18, 0x1000
	s_addc_u32 s19, s19, 0
	ds_read_b128 v[114:117], v63 offset:448
	s_waitcnt vmcnt(31) lgkmcnt(3)
	v_pk_fma_f32 v[40:41], v[118:119], v[106:107], v[40:41] op_sel:[0,1,0] op_sel_hi:[1,1,1]
	v_pk_fma_f32 v[42:43], v[120:121], v[106:107], v[42:43] op_sel:[0,1,0] op_sel_hi:[1,1,1]
	global_load_dword v107, v32, s[18:19]
	s_add_u32 s18, s18, 0x1000
	s_addc_u32 s19, s19, 0
	ds_read_b128 v[118:121], v63 offset:464
	s_waitcnt vmcnt(31) lgkmcnt(3)
	v_pk_fma_f32 v[40:41], v[122:123], v[108:109], v[40:41] op_sel_hi:[1,0,1]
	v_pk_fma_f32 v[42:43], v[124:125], v[108:109], v[42:43] op_sel_hi:[1,0,1]
	global_load_dword v108, v32, s[18:19]
	s_add_u32 s18, s18, 0x1000
	s_addc_u32 s19, s19, 0
	ds_read_b128 v[122:125], v63 offset:480
	s_waitcnt vmcnt(31) lgkmcnt(3)
	v_pk_fma_f32 v[40:41], v[126:127], v[108:109], v[40:41] op_sel:[0,1,0] op_sel_hi:[1,1,1]
	v_pk_fma_f32 v[42:43], v[128:129], v[108:109], v[42:43] op_sel:[0,1,0] op_sel_hi:[1,1,1]
	global_load_dword v109, v32, s[18:19]
	s_add_u32 s18, s18, 0x1000
	s_addc_u32 s19, s19, 0
	ds_read_b128 v[126:129], v63 offset:496
	s_waitcnt vmcnt(31) lgkmcnt(3)
	v_pk_fma_f32 v[40:41], v[114:115], v[110:111], v[40:41] op_sel_hi:[1,0,1]
	v_pk_fma_f32 v[42:43], v[116:117], v[110:111], v[42:43] op_sel_hi:[1,0,1]
	global_load_dword v110, v32, s[18:19]
	s_add_u32 s18, s18, 0x1000
	s_addc_u32 s19, s19, 0
	ds_read_b128 v[114:117], v63 offset:512
	s_waitcnt vmcnt(31) lgkmcnt(3)
	v_pk_fma_f32 v[40:41], v[118:119], v[110:111], v[40:41] op_sel:[0,1,0] op_sel_hi:[1,1,1]
	v_pk_fma_f32 v[42:43], v[120:121], v[110:111], v[42:43] op_sel:[0,1,0] op_sel_hi:[1,1,1]
	global_load_dword v111, v32, s[18:19]
	s_add_u32 s18, s18, 0x1000
	s_addc_u32 s19, s19, 0
	ds_read_b128 v[118:121], v63 offset:528
	s_waitcnt vmcnt(31) lgkmcnt(3)
	v_pk_fma_f32 v[40:41], v[122:123], v[112:113], v[40:41] op_sel_hi:[1,0,1]
	v_pk_fma_f32 v[42:43], v[124:125], v[112:113], v[42:43] op_sel_hi:[1,0,1]
	global_load_dword v112, v32, s[18:19]
	s_add_u32 s18, s18, 0x1000
	s_addc_u32 s19, s19, 0
	ds_read_b128 v[122:125], v63 offset:544
	s_waitcnt vmcnt(31) lgkmcnt(3)
	v_pk_fma_f32 v[40:41], v[126:127], v[112:113], v[40:41] op_sel:[0,1,0] op_sel_hi:[1,1,1]
	v_pk_fma_f32 v[42:43], v[128:129], v[112:113], v[42:43] op_sel:[0,1,0] op_sel_hi:[1,1,1]
	global_load_dword v113, v32, s[18:19]
	s_add_u32 s18, s18, 0x1000
	s_addc_u32 s19, s19, 0
	ds_read_b128 v[126:129], v63 offset:560
	s_waitcnt vmcnt(31) lgkmcnt(3)
	v_pk_fma_f32 v[40:41], v[114:115], v[82:83], v[40:41] op_sel_hi:[1,0,1]
	v_pk_fma_f32 v[42:43], v[116:117], v[82:83], v[42:43] op_sel_hi:[1,0,1]
	global_load_dword v82, v32, s[18:19]
	s_add_u32 s18, s18, 0x1000
	s_addc_u32 s19, s19, 0
	ds_read_b128 v[114:117], v63 offset:576
	s_waitcnt vmcnt(31) lgkmcnt(3)
	v_pk_fma_f32 v[40:41], v[118:119], v[82:83], v[40:41] op_sel:[0,1,0] op_sel_hi:[1,1,1]
	v_pk_fma_f32 v[42:43], v[120:121], v[82:83], v[42:43] op_sel:[0,1,0] op_sel_hi:[1,1,1]
	global_load_dword v83, v32, s[18:19]
	s_add_u32 s18, s18, 0x1000
	s_addc_u32 s19, s19, 0
	ds_read_b128 v[118:121], v63 offset:592
	s_waitcnt vmcnt(31) lgkmcnt(3)
	v_pk_fma_f32 v[40:41], v[122:123], v[84:85], v[40:41] op_sel_hi:[1,0,1]
	v_pk_fma_f32 v[42:43], v[124:125], v[84:85], v[42:43] op_sel_hi:[1,0,1]
	global_load_dword v84, v32, s[18:19]
	s_add_u32 s18, s18, 0x1000
	s_addc_u32 s19, s19, 0
	ds_read_b128 v[122:125], v63 offset:608
	s_waitcnt vmcnt(31) lgkmcnt(3)
	v_pk_fma_f32 v[40:41], v[126:127], v[84:85], v[40:41] op_sel:[0,1,0] op_sel_hi:[1,1,1]
	v_pk_fma_f32 v[42:43], v[128:129], v[84:85], v[42:43] op_sel:[0,1,0] op_sel_hi:[1,1,1]
	global_load_dword v85, v32, s[18:19]
	s_add_u32 s18, s18, 0x1000
	s_addc_u32 s19, s19, 0
	ds_read_b128 v[126:129], v63 offset:624
	s_waitcnt vmcnt(31) lgkmcnt(3)
	v_pk_fma_f32 v[40:41], v[114:115], v[86:87], v[40:41] op_sel_hi:[1,0,1]
	v_pk_fma_f32 v[42:43], v[116:117], v[86:87], v[42:43] op_sel_hi:[1,0,1]
	global_load_dword v86, v32, s[18:19]
	s_add_u32 s18, s18, 0x1000
	s_addc_u32 s19, s19, 0
	ds_read_b128 v[114:117], v63 offset:640
	s_waitcnt vmcnt(31) lgkmcnt(3)
	v_pk_fma_f32 v[40:41], v[118:119], v[86:87], v[40:41] op_sel:[0,1,0] op_sel_hi:[1,1,1]
	v_pk_fma_f32 v[42:43], v[120:121], v[86:87], v[42:43] op_sel:[0,1,0] op_sel_hi:[1,1,1]
	global_load_dword v87, v32, s[18:19]
	s_add_u32 s18, s18, 0x1000
	s_addc_u32 s19, s19, 0
	ds_read_b128 v[118:121], v63 offset:656
	s_waitcnt vmcnt(31) lgkmcnt(3)
; #define LAS __attribute__((address_space(3)))
; __global__ void __launch_bounds__(NTHREADS, 2) mk_fwd(Args args) {
;     ...
;                 for (int d0 = 0; d0 < 128; d0 += 32) {
;                     float wv[32];
; #pragma unroll
;                     for (int d = 0; d < 32; ++d) wv[d] = wpo[(size_t)(g * 128 + d0 + d) * DM + n];
; #pragma unroll
;                     for (int d = 0; d < 32; d += 4)
; #pragma unroll
;                         for (int j = 0; j < 4; ++j) { const f32x4 pv = *(const LAS f32x4*)(scr + j * 128 + d0 + d); a4[j] += (pv.x * wv[d] + pv.y * wv[d + 1]) + (pv.z * wv[d + 2] + pv.w * wv[d + 3]); } }
	v_pk_fma_f32 v[40:41], v[122:123], v[88:89], v[40:41] op_sel_hi:[1,0,1]
	v_pk_fma_f32 v[42:43], v[124:125], v[88:89], v[42:43] op_sel_hi:[1,0,1]
	global_load_dword v88, v32, s[18:19]
	s_add_u32 s18, s18, 0x1000
	s_addc_u32 s19, s19, 0
	ds_read_b128 v[122:125], v63 offset:672
	s_waitcnt vmcnt(31) lgkmcnt(3)
	v_pk_fma_f32 v[40:41], v[126:127], v[88:89], v[40:41] op_sel:[0,1,0] op_sel_hi:[1,1,1]
	v_pk_fma_f32 v[42:43], v[128:129], v[88:89], v[42:43] op_sel:[0,1,0] op_sel_hi:[1,1,1]
	global_load_dword v89, v32, s[18:19]
	s_add_u32 s18, s18, 0x1000
	s_addc_u32 s19, s19, 0
	ds_read_b128 v[126:129], v63 offset:688
	s_waitcnt vmcnt(31) lgkmcnt(3)
	v_pk_fma_f32 v[40:41], v[114:115], v[90:91], v[40:41] op_sel_hi:[1,0,1]
	v_pk_fma_f32 v[42:43], v[116:117], v[90:91], v[42:43] op_sel_hi:[1,0,1]
	global_load_dword v90, v32, s[18:19]
	s_add_u32 s18, s18, 0x1000
	s_addc_u32 s19, s19, 0
	ds_read_b128 v[114:117], v63 offset:704
	s_waitcnt vmcnt(31) lgkmcnt(3)
	v_pk_fma_f32 v[40:41], v[118:119], v[90:91], v[40:41] op_sel:[0,1,0] op_sel_hi:[1,1,1]
	v_pk_fma_f32 v[42:43], v[120:121], v[90:91], v[42:43] op_sel:[0,1,0] op_sel_hi:[1,1,1]
	global_load_dword v91, v32, s[18:19]
	s_add_u32 s18, s18, 0x1000
	s_addc_u32 s19, s19, 0
	ds_read_b128 v[118:121], v63 offset:720
	s_waitcnt vmcnt(31) lgkmcnt(3)
	v_pk_fma_f32 v[40:41], v[122:123], v[92:93], v[40:41] op_sel_hi:[1,0,1]
	v_pk_fma_f32 v[42:43], v[124:125], v[92:93], v[42:43] op_sel_hi:[1,0,1]
	global_load_dword v92, v32, s[18:19]
	s_add_u32 s18, s18, 0x1000
	s_addc_u32 s19, s19, 0
	ds_read_b128 v[122:125], v63 offset:736
	s_waitcnt vmcnt(31) lgkmcnt(3)
	v_pk_fma_f32 v[40:41], v[126:127], v[92:93], v[40:41] op_sel:[0,1,0] op_sel_hi:[1,1,1]
	v_pk_fma_f32 v[42:43], v[128:129], v[92:93], v[42:43] op_sel:[0,1,0] op_sel_hi:[1,1,1]
	global_load_dword v93, v32, s[18:19]
	s_add_u32 s18, s18, 0x1000
	s_addc_u32 s19, s19, 0
	ds_read_b128 v[126:129], v63 offset:752
	s_waitcnt vmcnt(31) lgkmcnt(3)
	v_pk_fma_f32 v[40:41], v[114:115], v[94:95], v[40:41] op_sel_hi:[1,0,1]
	v_pk_fma_f32 v[42:43], v[116:117], v[94:95], v[42:43] op_sel_hi:[1,0,1]
	global_load_dword v94, v32, s[18:19]
	s_add_u32 s18, s18, 0x1000
	s_addc_u32 s19, s19, 0
	ds_read_b128 v[114:117], v63 offset:768
	s_waitcnt vmcnt(31) lgkmcnt(3)
	v_pk_fma_f32 v[40:41], v[118:119], v[94:95], v[40:41] op_sel:[0,1,0] op_sel_hi:[1,1,1]
	v_pk_fma_f32 v[42:43], v[120:121], v[94:95], v[42:43] op_sel:[0,1,0] op_sel_hi:[1,1,1]
	global_load_dword v95, v32, s[18:19]
	s_add_u32 s18, s18, 0x1000
	s_addc_u32 s19, s19, 0
	ds_read_b128 v[118:121], v63 offset:784
	s_waitcnt vmcnt(31) lgkmcnt(3)
	v_pk_fma_f32 v[40:41], v[122:123], v[96:97], v[40:41] op_sel_hi:[1,0,1]
	v_pk_fma_f32 v[42:43], v[124:125], v[96:97], v[42:43] op_sel_hi:[1,0,1]
	global_load_dword v96, v32, s[18:19]
	s_add_u32 s18, s18, 0x1000
	s_addc_u32 s19, s19, 0
	ds_read_b128 v[122:125], v63 offset:800
	s_waitcnt vmcnt(31) lgkmcnt(3)
	v_pk_fma_f32 v[40:41], v[126:127], v[96:97], v[40:41] op_sel:[0,1,0] op_sel_hi:[1,1,1]
	v_pk_fma_f32 v[42:43], v[128:129], v[96:97], v[42:43] op_sel:[0,1,0] op_sel_hi:[1,1,1]
	global_load_dword v97, v32, s[18:19]
	s_add_u32 s18, s18, 0x1000
	s_addc_u32 s19, s19, 0
	ds_read_b128 v[126:129], v63 offset:816
	s_waitcnt vmcnt(31) lgkmcnt(3)
	v_pk_fma_f32 v[40:41], v[114:115], v[98:99], v[40:41] op_sel_hi:[1,0,1]
	v_pk_fma_f32 v[42:43], v[116:117], v[98:99], v[42:43] op_sel_hi:[1,0,1]
	global_load_dword v98, v32, s[18:19]
	s_add_u32 s18, s18, 0x1000
	s_addc_u32 s19, s19, 0
	ds_read_b128 v[114:117], v63 offset:832
	s_waitcnt vmcnt(31) lgkmcnt(3)
	v_pk_fma_f32 v[40:41], v[118:119], v[98:99], v[40:41] op_sel:[0,1,0] op_sel_hi:[1,1,1]
	v_pk_fma_f32 v[42:43], v[120:121], v[98:99], v[42:43] op_sel:[0,1,0] op_sel_hi:[1,1,1]
	global_load_dword v99, v32, s[18:19]
	s_add_u32 s18, s18, 0x1000
	s_addc_u32 s19, s19, 0
	ds_read_b128 v[118:121], v63 offset:848
	s_waitcnt vmcnt(31) lgkmcnt(3)
	v_pk_fma_f32 v[40:41], v[122:123], v[100:101], v[40:41] op_sel_hi:[1,0,1]
	v_pk_fma_f32 v[42:43], v[124:125], v[100:101], v[42:43] op_sel_hi:[1,0,1]
	global_load_dword v100, v32, s[18:19]
	s_add_u32 s18, s18, 0x1000
	s_addc_u32 s19, s19, 0
	ds_read_b128 v[122:125], v63 offset:864
	s_waitcnt vmcnt(31) lgkmcnt(3)
	v_pk_fma_f32 v[40:41], v[126:127], v[100:101], v[40:41] op_sel:[0,1,0] op_sel_hi:[1,1,1]
	v_pk_fma_f32 v[42:43], v[128:129], v[100:101], v[42:43] op_sel:[0,1,0] op_sel_hi:[1,1,1]
	global_load_dword v101, v32, s[18:19]
	s_add_u32 s18, s18, 0x1000
	s_addc_u32 s19, s19, 0
	ds_read_b128 v[126:129], v63 offset:880
	s_waitcnt vmcnt(31) lgkmcnt(3)
	v_pk_fma_f32 v[40:41], v[114:115], v[102:103], v[40:41] op_sel_hi:[1,0,1]
	v_pk_fma_f32 v[42:43], v[116:117], v[102:103], v[42:43] op_sel_hi:[1,0,1]
	global_load_dword v102, v32, s[18:19]
	s_add_u32 s18, s18, 0x1000
	s_addc_u32 s19, s19, 0
	ds_read_b128 v[114:117], v63 offset:896
	s_waitcnt vmcnt(31) lgkmcnt(3)
	v_pk_fma_f32 v[40:41], v[118:119], v[102:103], v[40:41] op_sel:[0,1,0] op_sel_hi:[1,1,1]
	v_pk_fma_f32 v[42:43], v[120:121], v[102:103], v[42:43] op_sel:[0,1,0] op_sel_hi:[1,1,1]
	global_load_dword v103, v32, s[18:19]
	s_add_u32 s18, s18, 0x1000
	s_addc_u32 s19, s19, 0
	ds_read_b128 v[118:121], v63 offset:912
	s_waitcnt vmcnt(31) lgkmcnt(3)
	v_pk_fma_f32 v[40:41], v[122:123], v[104:105], v[40:41] op_sel_hi:[1,0,1]
	v_pk_fma_f32 v[42:43], v[124:125], v[104:105], v[42:43] op_sel_hi:[1,0,1]
	global_load_dword v104, v32, s[18:19]
	s_add_u32 s18, s18, 0x1000
	s_addc_u32 s19, s19, 0
	ds_read_b128 v[122:125], v63 offset:928
	s_waitcnt vmcnt(31) lgkmcnt(3)
; #define LAS __attribute__((address_space(3)))
; __global__ void __launch_bounds__(NTHREADS, 2) mk_fwd(Args args) {
;     ...
;                 for (int d0 = 0; d0 < 128; d0 += 32) {
;                     float wv[32];
; #pragma unroll
;                     for (int d = 0; d < 32; ++d) wv[d] = wpo[(size_t)(g * 128 + d0 + d) * DM + n];
; #pragma unroll
;                     for (int d = 0; d < 32; d += 4)
; #pragma unroll
;                         for (int j = 0; j < 4; ++j) { const f32x4 pv = *(const LAS f32x4*)(scr + j * 128 + d0 + d); a4[j] += (pv.x * wv[d] + pv.y * wv[d + 1]) + (pv.z * wv[d + 2] + pv.w * wv[d + 3]); } }
	v_pk_fma_f32 v[40:41], v[126:127], v[104:105], v[40:41] op_sel:[0,1,0] op_sel_hi:[1,1,1]
	v_pk_fma_f32 v[42:43], v[128:129], v[104:105], v[42:43] op_sel:[0,1,0] op_sel_hi:[1,1,1]
	global_load_dword v105, v32, s[18:19]
	s_add_u32 s18, s18, 0x1000
	s_addc_u32 s19, s19, 0
	ds_read_b128 v[126:129], v63 offset:944
	s_waitcnt vmcnt(31) lgkmcnt(3)
	v_pk_fma_f32 v[40:41], v[114:115], v[106:107], v[40:41] op_sel_hi:[1,0,1]
	v_pk_fma_f32 v[42:43], v[116:117], v[106:107], v[42:43] op_sel_hi:[1,0,1]
	global_load_dword v106, v32, s[18:19]
	s_add_u32 s18, s18, 0x1000
	s_addc_u32 s19, s19, 0
	ds_read_b128 v[114:117], v63 offset:960
	s_waitcnt vmcnt(31) lgkmcnt(3)
	v_pk_fma_f32 v[40:41], v[118:119], v[106:107], v[40:41] op_sel:[0,1,0] op_sel_hi:[1,1,1]
	v_pk_fma_f32 v[42:43], v[120:121], v[106:107], v[42:43] op_sel:[0,1,0] op_sel_hi:[1,1,1]
	global_load_dword v107, v32, s[18:19]
	s_add_u32 s18, s18, 0x1000
	s_addc_u32 s19, s19, 0
	ds_read_b128 v[118:121], v63 offset:976
	s_waitcnt vmcnt(31) lgkmcnt(3)
	v_pk_fma_f32 v[40:41], v[122:123], v[108:109], v[40:41] op_sel_hi:[1,0,1]
	v_pk_fma_f32 v[42:43], v[124:125], v[108:109], v[42:43] op_sel_hi:[1,0,1]
	global_load_dword v108, v32, s[18:19]
	s_add_u32 s18, s18, 0x1000
	s_addc_u32 s19, s19, 0
	ds_read_b128 v[122:125], v63 offset:992
	s_waitcnt vmcnt(31) lgkmcnt(3)
	v_pk_fma_f32 v[40:41], v[126:127], v[108:109], v[40:41] op_sel:[0,1,0] op_sel_hi:[1,1,1]
	v_pk_fma_f32 v[42:43], v[128:129], v[108:109], v[42:43] op_sel:[0,1,0] op_sel_hi:[1,1,1]
	global_load_dword v109, v32, s[18:19]
	s_add_u32 s18, s18, 0x1000
	s_addc_u32 s19, s19, 0
	ds_read_b128 v[126:129], v63 offset:1008
	s_waitcnt vmcnt(31) lgkmcnt(3)
	v_pk_fma_f32 v[40:41], v[114:115], v[110:111], v[40:41] op_sel_hi:[1,0,1]
	v_pk_fma_f32 v[42:43], v[116:117], v[110:111], v[42:43] op_sel_hi:[1,0,1]
	global_load_dword v110, v32, s[18:19]
	s_add_u32 s18, s18, 0x1000
	s_addc_u32 s19, s19, 0
	ds_read_b128 v[114:117], v63 offset:1024
	s_waitcnt vmcnt(31) lgkmcnt(3)
	v_pk_fma_f32 v[40:41], v[118:119], v[110:111], v[40:41] op_sel:[0,1,0] op_sel_hi:[1,1,1]
	v_pk_fma_f32 v[42:43], v[120:121], v[110:111], v[42:43] op_sel:[0,1,0] op_sel_hi:[1,1,1]
	global_load_dword v111, v32, s[18:19]
	s_add_u32 s18, s18, 0x1000
	s_addc_u32 s19, s19, 0
	ds_read_b128 v[118:121], v63 offset:1040
	s_waitcnt vmcnt(31) lgkmcnt(3)
	v_pk_fma_f32 v[40:41], v[122:123], v[112:113], v[40:41] op_sel_hi:[1,0,1]
	v_pk_fma_f32 v[42:43], v[124:125], v[112:113], v[42:43] op_sel_hi:[1,0,1]
	global_load_dword v112, v32, s[18:19]
	s_add_u32 s18, s18, 0x1000
	s_addc_u32 s19, s19, 0
	ds_read_b128 v[122:125], v63 offset:1056
	s_waitcnt vmcnt(31) lgkmcnt(3)
	v_pk_fma_f32 v[40:41], v[126:127], v[112:113], v[40:41] op_sel:[0,1,0] op_sel_hi:[1,1,1]
	v_pk_fma_f32 v[42:43], v[128:129], v[112:113], v[42:43] op_sel:[0,1,0] op_sel_hi:[1,1,1]
	global_load_dword v113, v32, s[18:19]
	s_add_u32 s18, s18, 0x1000
	s_addc_u32 s19, s19, 0
	ds_read_b128 v[126:129], v63 offset:1072
	s_waitcnt vmcnt(31) lgkmcnt(3)
	v_pk_fma_f32 v[40:41], v[114:115], v[82:83], v[40:41] op_sel_hi:[1,0,1]
	v_pk_fma_f32 v[42:43], v[116:117], v[82:83], v[42:43] op_sel_hi:[1,0,1]
	global_load_dword v82, v32, s[18:19]
	s_add_u32 s18, s18, 0x1000
	s_addc_u32 s19, s19, 0
	ds_read_b128 v[114:117], v63 offset:1088
	s_waitcnt vmcnt(31) lgkmcnt(3)
	v_pk_fma_f32 v[40:41], v[118:119], v[82:83], v[40:41] op_sel:[0,1,0] op_sel_hi:[1,1,1]
	v_pk_fma_f32 v[42:43], v[120:121], v[82:83], v[42:43] op_sel:[0,1,0] op_sel_hi:[1,1,1]
	global_load_dword v83, v32, s[18:19]
	s_add_u32 s18, s18, 0x1000
	s_addc_u32 s19, s19, 0
	ds_read_b128 v[118:121], v63 offset:1104
	s_waitcnt vmcnt(31) lgkmcnt(3)
	v_pk_fma_f32 v[40:41], v[122:123], v[84:85], v[40:41] op_sel_hi:[1,0,1]
	v_pk_fma_f32 v[42:43], v[124:125], v[84:85], v[42:43] op_sel_hi:[1,0,1]
	global_load_dword v84, v32, s[18:19]
	s_add_u32 s18, s18, 0x1000
	s_addc_u32 s19, s19, 0
	ds_read_b128 v[122:125], v63 offset:1120
	s_waitcnt vmcnt(31) lgkmcnt(3)
	v_pk_fma_f32 v[40:41], v[126:127], v[84:85], v[40:41] op_sel:[0,1,0] op_sel_hi:[1,1,1]
	v_pk_fma_f32 v[42:43], v[128:129], v[84:85], v[42:43] op_sel:[0,1,0] op_sel_hi:[1,1,1]
	global_load_dword v85, v32, s[18:19]
	s_add_u32 s18, s18, 0x1000
	s_addc_u32 s19, s19, 0
	ds_read_b128 v[126:129], v63 offset:1136
	s_waitcnt vmcnt(31) lgkmcnt(3)
	v_pk_fma_f32 v[40:41], v[114:115], v[86:87], v[40:41] op_sel_hi:[1,0,1]
	v_pk_fma_f32 v[42:43], v[116:117], v[86:87], v[42:43] op_sel_hi:[1,0,1]
	global_load_dword v86, v32, s[18:19]
	s_add_u32 s18, s18, 0x1000
	s_addc_u32 s19, s19, 0
	ds_read_b128 v[114:117], v63 offset:1152
	s_waitcnt vmcnt(31) lgkmcnt(3)
	v_pk_fma_f32 v[40:41], v[118:119], v[86:87], v[40:41] op_sel:[0,1,0] op_sel_hi:[1,1,1]
	v_pk_fma_f32 v[42:43], v[120:121], v[86:87], v[42:43] op_sel:[0,1,0] op_sel_hi:[1,1,1]
	global_load_dword v87, v32, s[18:19]
	s_add_u32 s18, s18, 0x1000
	s_addc_u32 s19, s19, 0
	ds_read_b128 v[118:121], v63 offset:1168
	s_waitcnt vmcnt(31) lgkmcnt(3)
	v_pk_fma_f32 v[40:41], v[122:123], v[88:89], v[40:41] op_sel_hi:[1,0,1]
	v_pk_fma_f32 v[42:43], v[124:125], v[88:89], v[42:43] op_sel_hi:[1,0,1]
	global_load_dword v88, v32, s[18:19]
	s_add_u32 s18, s18, 0x1000
	s_addc_u32 s19, s19, 0
	ds_read_b128 v[122:125], v63 offset:1184
	s_waitcnt vmcnt(31) lgkmcnt(3)
	v_pk_fma_f32 v[40:41], v[126:127], v[88:89], v[40:41] op_sel:[0,1,0] op_sel_hi:[1,1,1]
	v_pk_fma_f32 v[42:43], v[128:129], v[88:89], v[42:43] op_sel:[0,1,0] op_sel_hi:[1,1,1]
	global_load_dword v89, v32, s[18:19]
	s_add_u32 s18, s18, 0x1000
	s_addc_u32 s19, s19, 0
	ds_read_b128 v[126:129], v63 offset:1200
	s_waitcnt vmcnt(31) lgkmcnt(3)
; #define LAS __attribute__((address_space(3)))
; __global__ void __launch_bounds__(NTHREADS, 2) mk_fwd(Args args) {
;     ...
;                 for (int d0 = 0; d0 < 128; d0 += 32) {
;                     float wv[32];
; #pragma unroll
;                     for (int d = 0; d < 32; ++d) wv[d] = wpo[(size_t)(g * 128 + d0 + d) * DM + n];
; #pragma unroll
;                     for (int d = 0; d < 32; d += 4)
; #pragma unroll
;                         for (int j = 0; j < 4; ++j) { const f32x4 pv = *(const LAS f32x4*)(scr + j * 128 + d0 + d); a4[j] += (pv.x * wv[d] + pv.y * wv[d + 1]) + (pv.z * wv[d + 2] + pv.w * wv[d + 3]); } }
	v_pk_fma_f32 v[40:41], v[114:115], v[90:91], v[40:41] op_sel_hi:[1,0,1]
	v_pk_fma_f32 v[42:43], v[116:117], v[90:91], v[42:43] op_sel_hi:[1,0,1]
	global_load_dword v90, v32, s[18:19]
	s_add_u32 s18, s18, 0x1000
	s_addc_u32 s19, s19, 0
	ds_read_b128 v[114:117], v63 offset:1216
	s_waitcnt vmcnt(31) lgkmcnt(3)
	v_pk_fma_f32 v[40:41], v[118:119], v[90:91], v[40:41] op_sel:[0,1,0] op_sel_hi:[1,1,1]
	v_pk_fma_f32 v[42:43], v[120:121], v[90:91], v[42:43] op_sel:[0,1,0] op_sel_hi:[1,1,1]
	global_load_dword v91, v32, s[18:19]
	s_add_u32 s18, s18, 0x1000
	s_addc_u32 s19, s19, 0
	ds_read_b128 v[118:121], v63 offset:1232
	s_waitcnt vmcnt(31) lgkmcnt(3)
	v_pk_fma_f32 v[40:41], v[122:123], v[92:93], v[40:41] op_sel_hi:[1,0,1]
	v_pk_fma_f32 v[42:43], v[124:125], v[92:93], v[42:43] op_sel_hi:[1,0,1]
	global_load_dword v92, v32, s[18:19]
	s_add_u32 s18, s18, 0x1000
	s_addc_u32 s19, s19, 0
	ds_read_b128 v[122:125], v63 offset:1248
	s_waitcnt vmcnt(31) lgkmcnt(3)
	v_pk_fma_f32 v[40:41], v[126:127], v[92:93], v[40:41] op_sel:[0,1,0] op_sel_hi:[1,1,1]
	v_pk_fma_f32 v[42:43], v[128:129], v[92:93], v[42:43] op_sel:[0,1,0] op_sel_hi:[1,1,1]
	global_load_dword v93, v32, s[18:19]
	s_add_u32 s18, s18, 0x1000
	s_addc_u32 s19, s19, 0
	ds_read_b128 v[126:129], v63 offset:1264
	s_waitcnt vmcnt(31) lgkmcnt(3)
	v_pk_fma_f32 v[40:41], v[114:115], v[94:95], v[40:41] op_sel_hi:[1,0,1]
	v_pk_fma_f32 v[42:43], v[116:117], v[94:95], v[42:43] op_sel_hi:[1,0,1]
	global_load_dword v94, v32, s[18:19]
	s_add_u32 s18, s18, 0x1000
	s_addc_u32 s19, s19, 0
	ds_read_b128 v[114:117], v63 offset:1280
	s_waitcnt vmcnt(31) lgkmcnt(3)
	v_pk_fma_f32 v[40:41], v[118:119], v[94:95], v[40:41] op_sel:[0,1,0] op_sel_hi:[1,1,1]
	v_pk_fma_f32 v[42:43], v[120:121], v[94:95], v[42:43] op_sel:[0,1,0] op_sel_hi:[1,1,1]
	global_load_dword v95, v32, s[18:19]
	s_add_u32 s18, s18, 0x1000
	s_addc_u32 s19, s19, 0
	ds_read_b128 v[118:121], v63 offset:1296
	s_waitcnt vmcnt(31) lgkmcnt(3)
	v_pk_fma_f32 v[40:41], v[122:123], v[96:97], v[40:41] op_sel_hi:[1,0,1]
	v_pk_fma_f32 v[42:43], v[124:125], v[96:97], v[42:43] op_sel_hi:[1,0,1]
	global_load_dword v96, v32, s[18:19]
	s_add_u32 s18, s18, 0x1000
	s_addc_u32 s19, s19, 0
	ds_read_b128 v[122:125], v63 offset:1312
	s_waitcnt vmcnt(31) lgkmcnt(3)
	v_pk_fma_f32 v[40:41], v[126:127], v[96:97], v[40:41] op_sel:[0,1,0] op_sel_hi:[1,1,1]
	v_pk_fma_f32 v[42:43], v[128:129], v[96:97], v[42:43] op_sel:[0,1,0] op_sel_hi:[1,1,1]
	global_load_dword v97, v32, s[18:19]
	s_add_u32 s18, s18, 0x1000
	s_addc_u32 s19, s19, 0
	ds_read_b128 v[126:129], v63 offset:1328
	s_waitcnt vmcnt(31) lgkmcnt(3)
	v_pk_fma_f32 v[40:41], v[114:115], v[98:99], v[40:41] op_sel_hi:[1,0,1]
	v_pk_fma_f32 v[42:43], v[116:117], v[98:99], v[42:43] op_sel_hi:[1,0,1]
	global_load_dword v98, v32, s[18:19]
	s_add_u32 s18, s18, 0x1000
	s_addc_u32 s19, s19, 0
	ds_read_b128 v[114:117], v63 offset:1344
	s_waitcnt vmcnt(31) lgkmcnt(3)
	v_pk_fma_f32 v[40:41], v[118:119], v[98:99], v[40:41] op_sel:[0,1,0] op_sel_hi:[1,1,1]
	v_pk_fma_f32 v[42:43], v[120:121], v[98:99], v[42:43] op_sel:[0,1,0] op_sel_hi:[1,1,1]
	global_load_dword v99, v32, s[18:19]
	s_add_u32 s18, s18, 0x1000
	s_addc_u32 s19, s19, 0
	ds_read_b128 v[118:121], v63 offset:1360
	s_waitcnt vmcnt(31) lgkmcnt(3)
	v_pk_fma_f32 v[40:41], v[122:123], v[100:101], v[40:41] op_sel_hi:[1,0,1]
	v_pk_fma_f32 v[42:43], v[124:125], v[100:101], v[42:43] op_sel_hi:[1,0,1]
	global_load_dword v100, v32, s[18:19]
	s_add_u32 s18, s18, 0x1000
	s_addc_u32 s19, s19, 0
	ds_read_b128 v[122:125], v63 offset:1376
	s_waitcnt vmcnt(31) lgkmcnt(3)
	v_pk_fma_f32 v[40:41], v[126:127], v[100:101], v[40:41] op_sel:[0,1,0] op_sel_hi:[1,1,1]
	v_pk_fma_f32 v[42:43], v[128:129], v[100:101], v[42:43] op_sel:[0,1,0] op_sel_hi:[1,1,1]
	global_load_dword v101, v32, s[18:19]
	s_add_u32 s18, s18, 0x1000
	s_addc_u32 s19, s19, 0
	ds_read_b128 v[126:129], v63 offset:1392
	s_waitcnt vmcnt(31) lgkmcnt(3)
	v_pk_fma_f32 v[40:41], v[114:115], v[102:103], v[40:41] op_sel_hi:[1,0,1]
	v_pk_fma_f32 v[42:43], v[116:117], v[102:103], v[42:43] op_sel_hi:[1,0,1]
	global_load_dword v102, v32, s[18:19]
	s_add_u32 s18, s18, 0x1000
	s_addc_u32 s19, s19, 0
	ds_read_b128 v[114:117], v63 offset:1408
	s_waitcnt vmcnt(31) lgkmcnt(3)
	v_pk_fma_f32 v[40:41], v[118:119], v[102:103], v[40:41] op_sel:[0,1,0] op_sel_hi:[1,1,1]
	v_pk_fma_f32 v[42:43], v[120:121], v[102:103], v[42:43] op_sel:[0,1,0] op_sel_hi:[1,1,1]
	global_load_dword v103, v32, s[18:19]
	s_add_u32 s18, s18, 0x1000
	s_addc_u32 s19, s19, 0
	ds_read_b128 v[118:121], v63 offset:1424
	s_waitcnt vmcnt(31) lgkmcnt(3)
	v_pk_fma_f32 v[40:41], v[122:123], v[104:105], v[40:41] op_sel_hi:[1,0,1]
	v_pk_fma_f32 v[42:43], v[124:125], v[104:105], v[42:43] op_sel_hi:[1,0,1]
	global_load_dword v104, v32, s[18:19]
	s_add_u32 s18, s18, 0x1000
	s_addc_u32 s19, s19, 0
	ds_read_b128 v[122:125], v63 offset:1440
	s_waitcnt vmcnt(31) lgkmcnt(3)
	v_pk_fma_f32 v[40:41], v[126:127], v[104:105], v[40:41] op_sel:[0,1,0] op_sel_hi:[1,1,1]
	v_pk_fma_f32 v[42:43], v[128:129], v[104:105], v[42:43] op_sel:[0,1,0] op_sel_hi:[1,1,1]
	global_load_dword v105, v32, s[18:19]
	s_add_u32 s18, s18, 0x1000
	s_addc_u32 s19, s19, 0
	ds_read_b128 v[126:129], v63 offset:1456
	s_waitcnt vmcnt(31) lgkmcnt(3)
	v_pk_fma_f32 v[40:41], v[114:115], v[106:107], v[40:41] op_sel_hi:[1,0,1]
	v_pk_fma_f32 v[42:43], v[116:117], v[106:107], v[42:43] op_sel_hi:[1,0,1]
	global_load_dword v106, v32, s[18:19]
	s_add_u32 s18, s18, 0x1000
	s_addc_u32 s19, s19, 0
	ds_read_b128 v[114:117], v63 offset:1472
	s_waitcnt vmcnt(31) lgkmcnt(3)
; #define LAS __attribute__((address_space(3)))
; __global__ void __launch_bounds__(NTHREADS, 2) mk_fwd(Args args) {
;     ...
;                 for (int d0 = 0; d0 < 128; d0 += 32) {
;                     float wv[32];
; #pragma unroll
;                     for (int d = 0; d < 32; ++d) wv[d] = wpo[(size_t)(g * 128 + d0 + d) * DM + n];
; #pragma unroll
;                     for (int d = 0; d < 32; d += 4)
; #pragma unroll
;                         for (int j = 0; j < 4; ++j) { const f32x4 pv = *(const LAS f32x4*)(scr + j * 128 + d0 + d); a4[j] += (pv.x * wv[d] + pv.y * wv[d + 1]) + (pv.z * wv[d + 2] + pv.w * wv[d + 3]); } }
	v_pk_fma_f32 v[40:41], v[118:119], v[106:107], v[40:41] op_sel:[0,1,0] op_sel_hi:[1,1,1]
	v_pk_fma_f32 v[42:43], v[120:121], v[106:107], v[42:43] op_sel:[0,1,0] op_sel_hi:[1,1,1]
	global_load_dword v107, v32, s[18:19]
	s_add_u32 s18, s18, 0x1000
	s_addc_u32 s19, s19, 0
	ds_read_b128 v[118:121], v63 offset:1488
	s_waitcnt vmcnt(31) lgkmcnt(3)
	v_pk_fma_f32 v[40:41], v[122:123], v[108:109], v[40:41] op_sel_hi:[1,0,1]
	v_pk_fma_f32 v[42:43], v[124:125], v[108:109], v[42:43] op_sel_hi:[1,0,1]
	global_load_dword v108, v32, s[18:19]
	s_add_u32 s18, s18, 0x1000
	s_addc_u32 s19, s19, 0
	ds_read_b128 v[122:125], v63 offset:1504
	s_waitcnt vmcnt(31) lgkmcnt(3)
	v_pk_fma_f32 v[40:41], v[126:127], v[108:109], v[40:41] op_sel:[0,1,0] op_sel_hi:[1,1,1]
	v_pk_fma_f32 v[42:43], v[128:129], v[108:109], v[42:43] op_sel:[0,1,0] op_sel_hi:[1,1,1]
	global_load_dword v109, v32, s[18:19]
	s_add_u32 s18, s18, 0x1000
	s_addc_u32 s19, s19, 0
	ds_read_b128 v[126:129], v63 offset:1520
	s_waitcnt vmcnt(31) lgkmcnt(3)
	v_pk_fma_f32 v[40:41], v[114:115], v[110:111], v[40:41] op_sel_hi:[1,0,1]
	v_pk_fma_f32 v[42:43], v[116:117], v[110:111], v[42:43] op_sel_hi:[1,0,1]
	global_load_dword v110, v32, s[18:19]
	s_add_u32 s18, s18, 0x1000
	s_addc_u32 s19, s19, 0
	ds_read_b128 v[114:117], v63 offset:1536
	s_waitcnt vmcnt(31) lgkmcnt(3)
	v_pk_fma_f32 v[40:41], v[118:119], v[110:111], v[40:41] op_sel:[0,1,0] op_sel_hi:[1,1,1]
	v_pk_fma_f32 v[42:43], v[120:121], v[110:111], v[42:43] op_sel:[0,1,0] op_sel_hi:[1,1,1]
	global_load_dword v111, v32, s[18:19]
	s_add_u32 s18, s18, 0x1000
	s_addc_u32 s19, s19, 0
	ds_read_b128 v[118:121], v63 offset:1552
	s_waitcnt vmcnt(31) lgkmcnt(3)
	v_pk_fma_f32 v[40:41], v[122:123], v[112:113], v[40:41] op_sel_hi:[1,0,1]
	v_pk_fma_f32 v[42:43], v[124:125], v[112:113], v[42:43] op_sel_hi:[1,0,1]
	global_load_dword v112, v32, s[18:19]
	s_add_u32 s18, s18, 0x1000
	s_addc_u32 s19, s19, 0
	ds_read_b128 v[122:125], v63 offset:1568
	s_waitcnt vmcnt(31) lgkmcnt(3)
	v_pk_fma_f32 v[40:41], v[126:127], v[112:113], v[40:41] op_sel:[0,1,0] op_sel_hi:[1,1,1]
	v_pk_fma_f32 v[42:43], v[128:129], v[112:113], v[42:43] op_sel:[0,1,0] op_sel_hi:[1,1,1]
	global_load_dword v113, v32, s[18:19]
	s_add_u32 s18, s18, 0x1000
	s_addc_u32 s19, s19, 0
	ds_read_b128 v[126:129], v63 offset:1584
	s_waitcnt vmcnt(31) lgkmcnt(3)
	v_pk_fma_f32 v[40:41], v[114:115], v[82:83], v[40:41] op_sel_hi:[1,0,1]
	v_pk_fma_f32 v[42:43], v[116:117], v[82:83], v[42:43] op_sel_hi:[1,0,1]
	ds_read_b128 v[114:117], v63 offset:1600
	s_waitcnt vmcnt(30) lgkmcnt(3)
	v_pk_fma_f32 v[40:41], v[118:119], v[82:83], v[40:41] op_sel:[0,1,0] op_sel_hi:[1,1,1]
	v_pk_fma_f32 v[42:43], v[120:121], v[82:83], v[42:43] op_sel:[0,1,0] op_sel_hi:[1,1,1]
	ds_read_b128 v[118:121], v63 offset:1616
	s_waitcnt vmcnt(29) lgkmcnt(3)
	v_pk_fma_f32 v[40:41], v[122:123], v[84:85], v[40:41] op_sel_hi:[1,0,1]
	v_pk_fma_f32 v[42:43], v[124:125], v[84:85], v[42:43] op_sel_hi:[1,0,1]
	ds_read_b128 v[122:125], v63 offset:1632
	s_waitcnt vmcnt(28) lgkmcnt(3)
	v_pk_fma_f32 v[40:41], v[126:127], v[84:85], v[40:41] op_sel:[0,1,0] op_sel_hi:[1,1,1]
	v_pk_fma_f32 v[42:43], v[128:129], v[84:85], v[42:43] op_sel:[0,1,0] op_sel_hi:[1,1,1]
	ds_read_b128 v[126:129], v63 offset:1648
	s_waitcnt vmcnt(27) lgkmcnt(3)
	v_pk_fma_f32 v[40:41], v[114:115], v[86:87], v[40:41] op_sel_hi:[1,0,1]
	v_pk_fma_f32 v[42:43], v[116:117], v[86:87], v[42:43] op_sel_hi:[1,0,1]
	ds_read_b128 v[114:117], v63 offset:1664
	s_waitcnt vmcnt(26) lgkmcnt(3)
	v_pk_fma_f32 v[40:41], v[118:119], v[86:87], v[40:41] op_sel:[0,1,0] op_sel_hi:[1,1,1]
	v_pk_fma_f32 v[42:43], v[120:121], v[86:87], v[42:43] op_sel:[0,1,0] op_sel_hi:[1,1,1]
	ds_read_b128 v[118:121], v63 offset:1680
	s_waitcnt vmcnt(25) lgkmcnt(3)
	v_pk_fma_f32 v[40:41], v[122:123], v[88:89], v[40:41] op_sel_hi:[1,0,1]
	v_pk_fma_f32 v[42:43], v[124:125], v[88:89], v[42:43] op_sel_hi:[1,0,1]
	ds_read_b128 v[122:125], v63 offset:1696
	s_waitcnt vmcnt(24) lgkmcnt(3)
	v_pk_fma_f32 v[40:41], v[126:127], v[88:89], v[40:41] op_sel:[0,1,0] op_sel_hi:[1,1,1]
	v_pk_fma_f32 v[42:43], v[128:129], v[88:89], v[42:43] op_sel:[0,1,0] op_sel_hi:[1,1,1]
	ds_read_b128 v[126:129], v63 offset:1712
	s_waitcnt vmcnt(23) lgkmcnt(3)
	v_pk_fma_f32 v[40:41], v[114:115], v[90:91], v[40:41] op_sel_hi:[1,0,1]
	v_pk_fma_f32 v[42:43], v[116:117], v[90:91], v[42:43] op_sel_hi:[1,0,1]
	ds_read_b128 v[114:117], v63 offset:1728
	s_waitcnt vmcnt(22) lgkmcnt(3)
	v_pk_fma_f32 v[40:41], v[118:119], v[90:91], v[40:41] op_sel:[0,1,0] op_sel_hi:[1,1,1]
	v_pk_fma_f32 v[42:43], v[120:121], v[90:91], v[42:43] op_sel:[0,1,0] op_sel_hi:[1,1,1]
	ds_read_b128 v[118:121], v63 offset:1744
	s_waitcnt vmcnt(21) lgkmcnt(3)
	v_pk_fma_f32 v[40:41], v[122:123], v[92:93], v[40:41] op_sel_hi:[1,0,1]
	v_pk_fma_f32 v[42:43], v[124:125], v[92:93], v[42:43] op_sel_hi:[1,0,1]
	ds_read_b128 v[122:125], v63 offset:1760
	s_waitcnt vmcnt(20) lgkmcnt(3)
	v_pk_fma_f32 v[40:41], v[126:127], v[92:93], v[40:41] op_sel:[0,1,0] op_sel_hi:[1,1,1]
	v_pk_fma_f32 v[42:43], v[128:129], v[92:93], v[42:43] op_sel:[0,1,0] op_sel_hi:[1,1,1]
	ds_read_b128 v[126:129], v63 offset:1776
	s_waitcnt vmcnt(19) lgkmcnt(3)
; #define LAS __attribute__((address_space(3)))
; #define LDS_WAIT() asm volatile("s_waitcnt lgkmcnt(0)" ::: "memory")
; __global__ void __launch_bounds__(NTHREADS, 2) mk_fwd(Args args) {
;     ...
;             for (int it = gw; it < 128 * 16; it += NGW) {
;                 const int kb = it >> 4, nb = it & 15, k0 = kb * 4, g = k0 >> 7, c0 = k0 & 127, n = nb * 64 + lane;
;     ...
;                 for (int d0 = 0; d0 < 128; d0 += 32) {
;                     float wv[32];
; #pragma unroll
;                     for (int d = 0; d < 32; ++d) wv[d] = wpo[(size_t)(g * 128 + d0 + d) * DM + n];
; #pragma unroll
;                     for (int d = 0; d < 32; d += 4)
; #pragma unroll
;                         for (int j = 0; j < 4; ++j) { const f32x4 pv = *(const LAS f32x4*)(scr + j * 128 + d0 + d); a4[j] += (pv.x * wv[d] + pv.y * wv[d + 1]) + (pv.z * wv[d + 2] + pv.w * wv[d + 3]); } }
;                 u32x2 o; o.x = rd<D_WMIX>(pk_f16(a4[0], a4[1])); o.y = rd<D_WMIX>(pk_f16(a4[2], a4[3]));
;                 *(u32x2*)((f16*)(ws + W_PC) + (size_t)n * DP + k0) = o;
;                 LDS_WAIT(); asm volatile("" ::: "memory");
	v_pk_fma_f32 v[40:41], v[114:115], v[94:95], v[40:41] op_sel_hi:[1,0,1]
	v_pk_fma_f32 v[42:43], v[116:117], v[94:95], v[42:43] op_sel_hi:[1,0,1]
	ds_read_b128 v[114:117], v63 offset:1792
	s_waitcnt vmcnt(18) lgkmcnt(3)
	v_pk_fma_f32 v[40:41], v[118:119], v[94:95], v[40:41] op_sel:[0,1,0] op_sel_hi:[1,1,1]
	v_pk_fma_f32 v[42:43], v[120:121], v[94:95], v[42:43] op_sel:[0,1,0] op_sel_hi:[1,1,1]
	ds_read_b128 v[118:121], v63 offset:1808
	s_waitcnt vmcnt(17) lgkmcnt(3)
	v_pk_fma_f32 v[40:41], v[122:123], v[96:97], v[40:41] op_sel_hi:[1,0,1]
	v_pk_fma_f32 v[42:43], v[124:125], v[96:97], v[42:43] op_sel_hi:[1,0,1]
	ds_read_b128 v[122:125], v63 offset:1824
	s_waitcnt vmcnt(16) lgkmcnt(3)
	v_pk_fma_f32 v[40:41], v[126:127], v[96:97], v[40:41] op_sel:[0,1,0] op_sel_hi:[1,1,1]
	v_pk_fma_f32 v[42:43], v[128:129], v[96:97], v[42:43] op_sel:[0,1,0] op_sel_hi:[1,1,1]
	ds_read_b128 v[126:129], v63 offset:1840
	s_waitcnt vmcnt(15) lgkmcnt(3)
	v_pk_fma_f32 v[40:41], v[114:115], v[98:99], v[40:41] op_sel_hi:[1,0,1]
	v_pk_fma_f32 v[42:43], v[116:117], v[98:99], v[42:43] op_sel_hi:[1,0,1]
	ds_read_b128 v[114:117], v63 offset:1856
	s_waitcnt vmcnt(14) lgkmcnt(3)
	v_pk_fma_f32 v[40:41], v[118:119], v[98:99], v[40:41] op_sel:[0,1,0] op_sel_hi:[1,1,1]
	v_pk_fma_f32 v[42:43], v[120:121], v[98:99], v[42:43] op_sel:[0,1,0] op_sel_hi:[1,1,1]
	ds_read_b128 v[118:121], v63 offset:1872
	s_waitcnt vmcnt(13) lgkmcnt(3)
	v_pk_fma_f32 v[40:41], v[122:123], v[100:101], v[40:41] op_sel_hi:[1,0,1]
	v_pk_fma_f32 v[42:43], v[124:125], v[100:101], v[42:43] op_sel_hi:[1,0,1]
	ds_read_b128 v[122:125], v63 offset:1888
	s_waitcnt vmcnt(12) lgkmcnt(3)
	v_pk_fma_f32 v[40:41], v[126:127], v[100:101], v[40:41] op_sel:[0,1,0] op_sel_hi:[1,1,1]
	v_pk_fma_f32 v[42:43], v[128:129], v[100:101], v[42:43] op_sel:[0,1,0] op_sel_hi:[1,1,1]
	ds_read_b128 v[126:129], v63 offset:1904
	s_waitcnt vmcnt(11) lgkmcnt(3)
	v_pk_fma_f32 v[40:41], v[114:115], v[102:103], v[40:41] op_sel_hi:[1,0,1]
	v_pk_fma_f32 v[42:43], v[116:117], v[102:103], v[42:43] op_sel_hi:[1,0,1]
	ds_read_b128 v[114:117], v63 offset:1920
	s_waitcnt vmcnt(10) lgkmcnt(3)
	v_pk_fma_f32 v[40:41], v[118:119], v[102:103], v[40:41] op_sel:[0,1,0] op_sel_hi:[1,1,1]
	v_pk_fma_f32 v[42:43], v[120:121], v[102:103], v[42:43] op_sel:[0,1,0] op_sel_hi:[1,1,1]
	ds_read_b128 v[118:121], v63 offset:1936
	s_waitcnt vmcnt(9) lgkmcnt(3)
	v_pk_fma_f32 v[40:41], v[122:123], v[104:105], v[40:41] op_sel_hi:[1,0,1]
	v_pk_fma_f32 v[42:43], v[124:125], v[104:105], v[42:43] op_sel_hi:[1,0,1]
	ds_read_b128 v[122:125], v63 offset:1952
	s_waitcnt vmcnt(8) lgkmcnt(3)
	v_pk_fma_f32 v[40:41], v[126:127], v[104:105], v[40:41] op_sel:[0,1,0] op_sel_hi:[1,1,1]
	v_pk_fma_f32 v[42:43], v[128:129], v[104:105], v[42:43] op_sel:[0,1,0] op_sel_hi:[1,1,1]
	ds_read_b128 v[126:129], v63 offset:1968
	s_waitcnt vmcnt(7) lgkmcnt(3)
	v_pk_fma_f32 v[40:41], v[114:115], v[106:107], v[40:41] op_sel_hi:[1,0,1]
	v_pk_fma_f32 v[42:43], v[116:117], v[106:107], v[42:43] op_sel_hi:[1,0,1]
	ds_read_b128 v[114:117], v63 offset:1984
	s_waitcnt vmcnt(6) lgkmcnt(3)
	v_pk_fma_f32 v[40:41], v[118:119], v[106:107], v[40:41] op_sel:[0,1,0] op_sel_hi:[1,1,1]
	v_pk_fma_f32 v[42:43], v[120:121], v[106:107], v[42:43] op_sel:[0,1,0] op_sel_hi:[1,1,1]
	ds_read_b128 v[118:121], v63 offset:2000
	s_waitcnt vmcnt(5) lgkmcnt(3)
	v_pk_fma_f32 v[40:41], v[122:123], v[108:109], v[40:41] op_sel_hi:[1,0,1]
	v_pk_fma_f32 v[42:43], v[124:125], v[108:109], v[42:43] op_sel_hi:[1,0,1]
	ds_read_b128 v[122:125], v63 offset:2016
	s_waitcnt vmcnt(4) lgkmcnt(3)
	v_pk_fma_f32 v[40:41], v[126:127], v[108:109], v[40:41] op_sel:[0,1,0] op_sel_hi:[1,1,1]
	v_pk_fma_f32 v[42:43], v[128:129], v[108:109], v[42:43] op_sel:[0,1,0] op_sel_hi:[1,1,1]
	ds_read_b128 v[126:129], v63 offset:2032
	s_waitcnt vmcnt(3) lgkmcnt(3)
	v_pk_fma_f32 v[40:41], v[114:115], v[110:111], v[40:41] op_sel_hi:[1,0,1]
	v_pk_fma_f32 v[42:43], v[116:117], v[110:111], v[42:43] op_sel_hi:[1,0,1]
	s_waitcnt vmcnt(2) lgkmcnt(2)
	v_pk_fma_f32 v[40:41], v[118:119], v[110:111], v[40:41] op_sel:[0,1,0] op_sel_hi:[1,1,1]
	v_pk_fma_f32 v[42:43], v[120:121], v[110:111], v[42:43] op_sel:[0,1,0] op_sel_hi:[1,1,1]
	s_waitcnt vmcnt(1) lgkmcnt(1)
	v_pk_fma_f32 v[40:41], v[122:123], v[112:113], v[40:41] op_sel_hi:[1,0,1]
	v_pk_fma_f32 v[42:43], v[124:125], v[112:113], v[42:43] op_sel_hi:[1,0,1]
	s_waitcnt vmcnt(0) lgkmcnt(0)
	v_pk_fma_f32 v[40:41], v[126:127], v[112:113], v[40:41] op_sel:[0,1,0] op_sel_hi:[1,1,1]
	v_pk_fma_f32 v[42:43], v[128:129], v[112:113], v[42:43] op_sel:[0,1,0] op_sel_hi:[1,1,1]
	s_lshl_b32 s17, s15, 3
	s_and_b32 s17, s17, 0x3c0
	v_or_b32_e32 v32, s17, v71
	v_readlane_b32 s18, v252, 1
	v_cvt_pk_f16_f32 v38, v40, v41
	v_cvt_pk_f16_f32 v39, v42, v43
	v_lshlrev_b32_e32 v32, 10, v32
	v_readlane_b32 s19, v252, 2
	v_add_u32_e32 v38, 0x100010, v38
	v_add_u32_e32 v39, 0x100010, v39
	v_lshl_add_u64 v[40:41], s[18:19], 0, v[32:33]
	v_and_b32_e32 v38, 0xffe0ffe0, v38
	v_and_b32_e32 v39, 0xffe0ffe0, v39
	v_lshl_add_u64 v[40:41], s[2:3], 1, v[40:41]
	global_store_dwordx2 v[40:41], v[38:39], off
	s_waitcnt lgkmcnt(0)
	s_add_i32 s15, s15, s64
	s_add_i32 s14, s14, s78
	s_cmpk_gt_i32 s15, 0x7ff
	s_cbranch_scc0 .LBB0_617
